# sc1 write-through on GEMM1 epilogue stores
# baseline (speedup 1.0000x reference)
; __device__ __forceinline__ unsigned cvt_pk_bf16(float lo, float hi) { f32x2_t v = {lo, hi}; bf16x2_t b = __builtin_convertvector(v, bf16x2_t); return __builtin_bit_cast(unsigned, b); }
; #define EPI_FENCE() asm volatile("" ::: "memory")
; #define EPI_LANE() int t__ = threadIdx.x; asm volatile("" : "+v"(t__)); const int wid__ = __builtin_amdgcn_readfirstlane(t__ >> 6); wr = wid__ >> 2; wc = wid__ & 3; fr = t__ & 15; fq = (t__ & 63) >> 4
;     template <int MODE> __device__ __forceinline__ void run(const f32x4 (&acc)[2][2][4][2], const Unit& u, int wr, int wc, int fr, int fq) const {
;         EPI_LANE();
;         const int pn = u.pn, colt = pn * BM, t = colt >> 9;
;         char* base = (MODE == 2) ? (char*)(O + (size_t)6 * ((size_t)MTOK * 512)) + ((size_t)(((pn - 12) * 128 + u.pm) * 8 + wid__)) * 16384
;                                  : (char*)(O + (size_t)t * ((size_t)MTOK * 512) + (size_t)u.pm * BM * 512 + (colt & 511));
;         unsigned off0 = (MODE == 2) ? (unsigned)((t__ & 63) * 16) : (unsigned)((wr * 64 + fr) * 512 + wc * 32 + 8 * fq) * 2u; asm volatile("" : "+v"(off0));
; #pragma unroll
;         for (int bj = 0; bj < 2; ++bj) {
; #pragma unroll
;             for (int ai = 0; ai < 2; ++ai)
; #pragma unroll
;                 for (int m = 0; m < 4; ++m) { const unsigned off = off0 + ((MODE == 2) ? (unsigned)(((ai * 4 + m) * 2 + bj) * 1024) : (unsigned)((ai * HALF + m * 16) * 512 + bj * HALF) * 2u);
;                     const f32x4 v0 = acc[ai][bj][m][0], v1 = acc[ai][bj][m][1];
;                     u32x4 w; w.x = cvt_pk_bf16(actf<MODE>(v0[0]), actf<MODE>(v0[1])); w.y = cvt_pk_bf16(actf<MODE>(v0[2]), actf<MODE>(v0[3]));
;                     w.z = cvt_pk_bf16(actf<MODE>(v1[0]), actf<MODE>(v1[1])); w.w = cvt_pk_bf16(actf<MODE>(v1[2]), actf<MODE>(v1[3]));
;                     *(u32x4*)(base + off) = w; }
;             EPI_FENCE();
;         }
;     }
.LBB0_403:
	v_mul_f32_e32 v12, 0xbfb8aa3b, v12
	v_mul_f32_e32 v13, 0xbfb8aa3b, v13
	v_exp_f32_e32 v12, v12
	v_exp_f32_e32 v13, v13
	v_mul_f32_e32 v14, 0xbfb8aa3b, v14
	v_mul_f32_e32 v15, 0xbfb8aa3b, v15
	v_mul_f32_e32 v8, 0xbfb8aa3b, v8
	v_mul_f32_e32 v9, 0xbfb8aa3b, v9
	v_exp_f32_e32 v14, v14
	v_exp_f32_e32 v15, v15
	v_exp_f32_e32 v8, v8
	v_exp_f32_e32 v9, v9
	v_mul_f32_e32 v10, 0xbfb8aa3b, v10
	v_mul_f32_e32 v11, 0xbfb8aa3b, v11
	v_add_f32_e32 v12, 1.0, v12
	v_add_f32_e32 v13, 1.0, v13
	v_exp_f32_e32 v10, v10
	v_exp_f32_e32 v11, v11
	v_mul_f32_e32 v76, 0xbfb8aa3b, v76
	v_mul_f32_e32 v77, 0xbfb8aa3b, v77
	v_min_f32_e32 v12, 0x7149f2ca, v12
	v_min_f32_e32 v13, 0x7149f2ca, v13
	v_exp_f32_e32 v76, v76
	v_exp_f32_e32 v77, v77
	v_cvt_pk_bf16_f32 v12, v12, v13
	v_add_f32_e32 v13, 1.0, v14
	v_add_f32_e32 v14, 1.0, v15
	v_add_f32_e32 v8, 1.0, v8
	v_add_f32_e32 v9, 1.0, v9
	v_mul_f32_e32 v78, 0xbfb8aa3b, v78
	v_mul_f32_e32 v79, 0xbfb8aa3b, v79
	v_mul_f32_e32 v72, 0xbfb8aa3b, v72
	v_mul_f32_e32 v73, 0xbfb8aa3b, v73
	v_min_f32_e32 v13, 0x7149f2ca, v13
	v_min_f32_e32 v14, 0x7149f2ca, v14
	v_min_f32_e32 v8, 0x7149f2ca, v8
	v_min_f32_e32 v9, 0x7149f2ca, v9
	v_mov_b32_e32 v142, v212
	s_lshl_b32 s60, s72, 7
	v_exp_f32_e32 v78, v78
	v_exp_f32_e32 v79, v79
	v_exp_f32_e32 v72, v72
	v_exp_f32_e32 v73, v73
	v_cvt_pk_bf16_f32 v13, v13, v14
	v_cvt_pk_bf16_f32 v14, v8, v9
	v_add_f32_e32 v8, 1.0, v10
	v_add_f32_e32 v9, 1.0, v11
	s_add_i32 s60, s60, s54
	v_readfirstlane_b32 s55, v142
	v_mul_f32_e32 v74, 0xbfb8aa3b, v74
	v_mul_f32_e32 v75, 0xbfb8aa3b, v75
	v_min_f32_e32 v8, 0x7149f2ca, v8
	v_min_f32_e32 v9, 0x7149f2ca, v9
	s_ashr_i32 s55, s55, 6
	s_lshl_b32 s54, s60, 3
	v_add_f32_e32 v76, 1.0, v76
	v_add_f32_e32 v77, 1.0, v77
	v_exp_f32_e32 v74, v74
	v_exp_f32_e32 v75, v75
	v_cvt_pk_bf16_f32 v15, v8, v9
	v_mul_f32_e32 v8, 0xbfb8aa3b, v68
	v_mul_f32_e32 v9, 0xbfb8aa3b, v69
	s_add_i32 s54, s54, s55
	v_min_f32_e32 v76, 0x7149f2ca, v76
	v_min_f32_e32 v77, 0x7149f2ca, v77
	v_exp_f32_e32 v8, v8
	v_exp_f32_e32 v9, v9
	s_addk_i32 s54, 0xd000
	v_cvt_pk_bf16_f32 v76, v76, v77
	v_add_f32_e32 v77, 1.0, v78
	v_add_f32_e32 v78, 1.0, v79
	v_add_f32_e32 v72, 1.0, v72
	v_add_f32_e32 v73, 1.0, v73
	v_mul_f32_e32 v10, 0xbfb8aa3b, v70
	v_mul_f32_e32 v11, 0xbfb8aa3b, v71
	s_ashr_i32 s55, s54, 31
	v_min_f32_e32 v77, 0x7149f2ca, v77
	v_min_f32_e32 v78, 0x7149f2ca, v78
	v_min_f32_e32 v72, 0x7149f2ca, v72
	v_min_f32_e32 v73, 0x7149f2ca, v73
	v_exp_f32_e32 v10, v10
	v_exp_f32_e32 v11, v11
	s_lshl_b64 s[54:55], s[54:55], 14
	v_lshlrev_b32_e32 v142, 4, v142
	v_cvt_pk_bf16_f32 v77, v77, v78
	v_cvt_pk_bf16_f32 v78, v72, v73
	v_add_f32_e32 v72, 1.0, v74
	v_add_f32_e32 v73, 1.0, v75
	s_add_u32 s54, s33, s54
	v_and_b32_e32 v142, 0x3f0, v142
	v_min_f32_e32 v72, 0x7149f2ca, v72
	v_min_f32_e32 v73, 0x7149f2ca, v73
	v_add_f32_e32 v8, 1.0, v8
	v_add_f32_e32 v9, 1.0, v9
	s_addc_u32 s55, s37, s55
	v_cvt_pk_bf16_f32 v79, v72, v73
	v_add_u32_e32 v72, 0x3800, v142
	v_min_f32_e32 v8, 0x7149f2ca, v8
	v_min_f32_e32 v9, 0x7149f2ca, v9
	v_mul_f32_e32 v126, 0xbfb8aa3b, v126
	v_mul_f32_e32 v127, 0xbfb8aa3b, v127
	v_mul_f32_e32 v118, 0xbfb8aa3b, v118
	v_mul_f32_e32 v119, 0xbfb8aa3b, v119
	v_mul_f32_e32 v110, 0xbfb8aa3b, v110
	v_mul_f32_e32 v111, 0xbfb8aa3b, v111
	v_mul_f32_e32 v102, 0xbfb8aa3b, v102
	v_mul_f32_e32 v103, 0xbfb8aa3b, v103
	v_mul_f32_e32 v92, 0xbfb8aa3b, v92
	v_mul_f32_e32 v93, 0xbfb8aa3b, v93
	v_mul_f32_e32 v84, 0xbfb8aa3b, v84
	v_mul_f32_e32 v85, 0xbfb8aa3b, v85
	global_store_dwordx4 v72, v[12:15], s[54:55] sc1
	v_cvt_pk_bf16_f32 v8, v8, v9
	v_add_f32_e32 v9, 1.0, v10
	v_add_f32_e32 v10, 1.0, v11
	v_mul_f32_e32 v11, 0xbfb8aa3b, v64
	v_mul_f32_e32 v13, 0xbfb8aa3b, v65
	v_exp_f32_e32 v126, v126
	v_exp_f32_e32 v127, v127
	v_exp_f32_e32 v118, v118
	v_exp_f32_e32 v119, v119
	v_exp_f32_e32 v110, v110
	v_exp_f32_e32 v111, v111
	v_exp_f32_e32 v102, v102
	v_exp_f32_e32 v103, v103
	v_exp_f32_e32 v92, v92
	v_exp_f32_e32 v93, v93
	v_exp_f32_e32 v84, v84
	v_exp_f32_e32 v85, v85
	v_exp_f32_e32 v11, v11
	v_exp_f32_e32 v13, v13
	v_mul_f32_e32 v128, 0xbfb8aa3b, v128
	v_mul_f32_e32 v129, 0xbfb8aa3b, v129
	v_mul_f32_e32 v122, 0xbfb8aa3b, v122
	v_mul_f32_e32 v123, 0xbfb8aa3b, v123
	v_mul_f32_e32 v120, 0xbfb8aa3b, v120
	v_mul_f32_e32 v121, 0xbfb8aa3b, v121
	v_mul_f32_e32 v114, 0xbfb8aa3b, v114
	v_mul_f32_e32 v115, 0xbfb8aa3b, v115
	v_mul_f32_e32 v112, 0xbfb8aa3b, v112
	v_mul_f32_e32 v113, 0xbfb8aa3b, v113
	v_mul_f32_e32 v106, 0xbfb8aa3b, v106
	v_mul_f32_e32 v107, 0xbfb8aa3b, v107
	v_mul_f32_e32 v104, 0xbfb8aa3b, v104
	v_mul_f32_e32 v105, 0xbfb8aa3b, v105
	v_mul_f32_e32 v98, 0xbfb8aa3b, v98
	v_mul_f32_e32 v99, 0xbfb8aa3b, v99
	v_mul_f32_e32 v94, 0xbfb8aa3b, v94
	v_mul_f32_e32 v95, 0xbfb8aa3b, v95
	v_mul_f32_e32 v88, 0xbfb8aa3b, v88
	v_mul_f32_e32 v89, 0xbfb8aa3b, v89
	v_mul_f32_e32 v86, 0xbfb8aa3b, v86
	v_mul_f32_e32 v87, 0xbfb8aa3b, v87
	v_mul_f32_e32 v80, 0xbfb8aa3b, v80
	v_mul_f32_e32 v81, 0xbfb8aa3b, v81
	v_exp_f32_e32 v128, v128
	v_exp_f32_e32 v129, v129
	v_exp_f32_e32 v122, v122
	v_exp_f32_e32 v123, v123
	v_exp_f32_e32 v120, v120
	v_exp_f32_e32 v121, v121
	v_exp_f32_e32 v114, v114
	v_exp_f32_e32 v115, v115
	v_exp_f32_e32 v112, v112
	v_exp_f32_e32 v113, v113
	v_exp_f32_e32 v106, v106
	v_exp_f32_e32 v107, v107
	v_exp_f32_e32 v104, v104
	v_exp_f32_e32 v105, v105
	v_exp_f32_e32 v98, v98
	v_exp_f32_e32 v99, v99
	v_exp_f32_e32 v94, v94
	v_exp_f32_e32 v95, v95
	v_exp_f32_e32 v88, v88
	v_exp_f32_e32 v89, v89
	v_exp_f32_e32 v86, v86
	v_exp_f32_e32 v87, v87
	v_exp_f32_e32 v80, v80
	v_exp_f32_e32 v81, v81
	v_mul_f32_e32 v124, 0xbfb8aa3b, v124
	v_mul_f32_e32 v125, 0xbfb8aa3b, v125
	v_mul_f32_e32 v116, 0xbfb8aa3b, v116
; __device__ __forceinline__ unsigned cvt_pk_bf16(float lo, float hi) { f32x2_t v = {lo, hi}; bf16x2_t b = __builtin_convertvector(v, bf16x2_t); return __builtin_bit_cast(unsigned, b); }
; #define EPI_FENCE() asm volatile("" ::: "memory")
; #define EPI_LANE() int t__ = threadIdx.x; asm volatile("" : "+v"(t__)); const int wid__ = __builtin_amdgcn_readfirstlane(t__ >> 6); wr = wid__ >> 2; wc = wid__ & 3; fr = t__ & 15; fq = (t__ & 63) >> 4
;     template <int MODE> __device__ __forceinline__ void run(const f32x4 (&acc)[2][2][4][2], const Unit& u, int wr, int wc, int fr, int fq) const {
;         EPI_LANE();
;         const int pn = u.pn, colt = pn * BM, t = colt >> 9;
;         char* base = (MODE == 2) ? (char*)(O + (size_t)6 * ((size_t)MTOK * 512)) + ((size_t)(((pn - 12) * 128 + u.pm) * 8 + wid__)) * 16384
;                                  : (char*)(O + (size_t)t * ((size_t)MTOK * 512) + (size_t)u.pm * BM * 512 + (colt & 511));
;         unsigned off0 = (MODE == 2) ? (unsigned)((t__ & 63) * 16) : (unsigned)((wr * 64 + fr) * 512 + wc * 32 + 8 * fq) * 2u; asm volatile("" : "+v"(off0));
; #pragma unroll
;         for (int bj = 0; bj < 2; ++bj) {
; #pragma unroll
;             for (int ai = 0; ai < 2; ++ai)
; #pragma unroll
;                 for (int m = 0; m < 4; ++m) { const unsigned off = off0 + ((MODE == 2) ? (unsigned)(((ai * 4 + m) * 2 + bj) * 1024) : (unsigned)((ai * HALF + m * 16) * 512 + bj * HALF) * 2u);
;                     const f32x4 v0 = acc[ai][bj][m][0], v1 = acc[ai][bj][m][1];
;                     u32x4 w; w.x = cvt_pk_bf16(actf<MODE>(v0[0]), actf<MODE>(v0[1])); w.y = cvt_pk_bf16(actf<MODE>(v0[2]), actf<MODE>(v0[3]));
;                     w.z = cvt_pk_bf16(actf<MODE>(v1[0]), actf<MODE>(v1[1])); w.w = cvt_pk_bf16(actf<MODE>(v1[2]), actf<MODE>(v1[3]));
;                     *(u32x4*)(base + off) = w; }
;             EPI_FENCE();
;         }
;     }
	v_mul_f32_e32 v117, 0xbfb8aa3b, v117
	v_mul_f32_e32 v108, 0xbfb8aa3b, v108
	v_mul_f32_e32 v109, 0xbfb8aa3b, v109
	v_mul_f32_e32 v100, 0xbfb8aa3b, v100
	v_mul_f32_e32 v101, 0xbfb8aa3b, v101
	v_mul_f32_e32 v90, 0xbfb8aa3b, v90
	v_mul_f32_e32 v91, 0xbfb8aa3b, v91
	v_mul_f32_e32 v82, 0xbfb8aa3b, v82
	v_mul_f32_e32 v83, 0xbfb8aa3b, v83
	v_min_f32_e32 v9, 0x7149f2ca, v9
	v_min_f32_e32 v10, 0x7149f2ca, v10
	v_add_f32_e32 v126, 1.0, v126
	v_add_f32_e32 v127, 1.0, v127
	v_exp_f32_e32 v124, v124
	v_exp_f32_e32 v125, v125
	v_add_f32_e32 v118, 1.0, v118
	v_add_f32_e32 v119, 1.0, v119
	v_exp_f32_e32 v116, v116
	v_exp_f32_e32 v117, v117
	v_add_f32_e32 v110, 1.0, v110
	v_add_f32_e32 v111, 1.0, v111
	v_exp_f32_e32 v108, v108
	v_exp_f32_e32 v109, v109
	v_add_f32_e32 v102, 1.0, v102
	v_add_f32_e32 v103, 1.0, v103
	v_exp_f32_e32 v100, v100
	v_exp_f32_e32 v101, v101
	v_add_f32_e32 v92, 1.0, v92
	v_add_f32_e32 v93, 1.0, v93
	v_exp_f32_e32 v90, v90
	v_exp_f32_e32 v91, v91
	v_add_f32_e32 v84, 1.0, v84
	v_add_f32_e32 v85, 1.0, v85
	v_exp_f32_e32 v82, v82
	v_exp_f32_e32 v83, v83
	v_cvt_pk_bf16_f32 v9, v9, v10
	v_add_f32_e32 v10, 1.0, v11
	v_add_f32_e32 v11, 1.0, v13
	v_mul_f32_e32 v13, 0xbfb8aa3b, v66
	v_mul_f32_e32 v14, 0xbfb8aa3b, v67
	v_min_f32_e32 v126, 0x7149f2ca, v126
	v_min_f32_e32 v127, 0x7149f2ca, v127
	v_min_f32_e32 v118, 0x7149f2ca, v118
	v_min_f32_e32 v119, 0x7149f2ca, v119
	v_min_f32_e32 v110, 0x7149f2ca, v110
	v_min_f32_e32 v111, 0x7149f2ca, v111
	v_min_f32_e32 v102, 0x7149f2ca, v102
	v_min_f32_e32 v103, 0x7149f2ca, v103
	v_min_f32_e32 v92, 0x7149f2ca, v92
	v_min_f32_e32 v93, 0x7149f2ca, v93
	v_min_f32_e32 v84, 0x7149f2ca, v84
	v_min_f32_e32 v85, 0x7149f2ca, v85
	v_exp_f32_e32 v13, v13
	v_exp_f32_e32 v14, v14
	v_cvt_pk_bf16_f32 v126, v126, v127
	v_add_f32_e32 v127, 1.0, v128
	v_add_f32_e32 v128, 1.0, v129
	v_add_f32_e32 v122, 1.0, v122
	v_add_f32_e32 v123, 1.0, v123
	v_cvt_pk_bf16_f32 v118, v118, v119
	v_add_f32_e32 v119, 1.0, v120
	v_add_f32_e32 v120, 1.0, v121
	v_add_f32_e32 v114, 1.0, v114
	v_add_f32_e32 v115, 1.0, v115
	v_cvt_pk_bf16_f32 v110, v110, v111
	v_add_f32_e32 v111, 1.0, v112
	v_add_f32_e32 v112, 1.0, v113
	v_add_f32_e32 v106, 1.0, v106
	v_add_f32_e32 v107, 1.0, v107
	v_cvt_pk_bf16_f32 v102, v102, v103
	v_add_f32_e32 v103, 1.0, v104
	v_add_f32_e32 v104, 1.0, v105
	v_add_f32_e32 v98, 1.0, v98
	v_add_f32_e32 v99, 1.0, v99
	v_cvt_pk_bf16_f32 v92, v92, v93
	v_add_f32_e32 v93, 1.0, v94
	v_add_f32_e32 v94, 1.0, v95
	v_add_f32_e32 v88, 1.0, v88
	v_add_f32_e32 v89, 1.0, v89
	v_cvt_pk_bf16_f32 v84, v84, v85
	v_add_f32_e32 v85, 1.0, v86
	v_add_f32_e32 v86, 1.0, v87
	v_add_f32_e32 v80, 1.0, v80
	v_add_f32_e32 v81, 1.0, v81
	v_min_f32_e32 v127, 0x7149f2ca, v127
	v_min_f32_e32 v128, 0x7149f2ca, v128
	v_min_f32_e32 v122, 0x7149f2ca, v122
	v_min_f32_e32 v123, 0x7149f2ca, v123
	v_min_f32_e32 v119, 0x7149f2ca, v119
	v_min_f32_e32 v120, 0x7149f2ca, v120
	v_min_f32_e32 v114, 0x7149f2ca, v114
	v_min_f32_e32 v115, 0x7149f2ca, v115
	v_min_f32_e32 v111, 0x7149f2ca, v111
	v_min_f32_e32 v112, 0x7149f2ca, v112
	v_min_f32_e32 v106, 0x7149f2ca, v106
	v_min_f32_e32 v107, 0x7149f2ca, v107
	v_min_f32_e32 v103, 0x7149f2ca, v103
	v_min_f32_e32 v104, 0x7149f2ca, v104
	v_min_f32_e32 v98, 0x7149f2ca, v98
	v_min_f32_e32 v99, 0x7149f2ca, v99
	v_min_f32_e32 v93, 0x7149f2ca, v93
	v_min_f32_e32 v94, 0x7149f2ca, v94
	v_min_f32_e32 v88, 0x7149f2ca, v88
	v_min_f32_e32 v89, 0x7149f2ca, v89
	v_min_f32_e32 v85, 0x7149f2ca, v85
	v_min_f32_e32 v86, 0x7149f2ca, v86
	v_min_f32_e32 v80, 0x7149f2ca, v80
	v_min_f32_e32 v81, 0x7149f2ca, v81
	v_cvt_pk_bf16_f32 v127, v127, v128
	v_cvt_pk_bf16_f32 v128, v122, v123
	v_add_f32_e32 v122, 1.0, v124
	v_add_f32_e32 v123, 1.0, v125
	v_cvt_pk_bf16_f32 v119, v119, v120
	v_cvt_pk_bf16_f32 v120, v114, v115
	v_add_f32_e32 v114, 1.0, v116
	v_add_f32_e32 v115, 1.0, v117
	v_cvt_pk_bf16_f32 v111, v111, v112
	v_cvt_pk_bf16_f32 v112, v106, v107
	v_add_f32_e32 v106, 1.0, v108
	v_add_f32_e32 v107, 1.0, v109
	v_cvt_pk_bf16_f32 v103, v103, v104
	v_cvt_pk_bf16_f32 v104, v98, v99
	v_add_f32_e32 v98, 1.0, v100
	v_add_f32_e32 v99, 1.0, v101
	v_cvt_pk_bf16_f32 v93, v93, v94
	v_cvt_pk_bf16_f32 v94, v88, v89
	v_add_f32_e32 v88, 1.0, v90
	v_add_f32_e32 v89, 1.0, v91
	v_cvt_pk_bf16_f32 v85, v85, v86
	v_cvt_pk_bf16_f32 v86, v80, v81
	v_add_f32_e32 v80, 1.0, v82
	v_add_f32_e32 v81, 1.0, v83
	v_min_f32_e32 v10, 0x7149f2ca, v10
	v_min_f32_e32 v11, 0x7149f2ca, v11
	v_min_f32_e32 v122, 0x7149f2ca, v122
	v_min_f32_e32 v123, 0x7149f2ca, v123
	v_min_f32_e32 v114, 0x7149f2ca, v114
	v_min_f32_e32 v115, 0x7149f2ca, v115
	v_min_f32_e32 v106, 0x7149f2ca, v106
	v_min_f32_e32 v107, 0x7149f2ca, v107
	v_min_f32_e32 v98, 0x7149f2ca, v98
	v_min_f32_e32 v99, 0x7149f2ca, v99
	v_min_f32_e32 v88, 0x7149f2ca, v88
	v_min_f32_e32 v89, 0x7149f2ca, v89
	v_min_f32_e32 v80, 0x7149f2ca, v80
	v_min_f32_e32 v81, 0x7149f2ca, v81
	v_cvt_pk_bf16_f32 v10, v10, v11
	v_add_f32_e32 v11, 1.0, v13
	v_add_f32_e32 v13, 1.0, v14
	v_cvt_pk_bf16_f32 v129, v122, v123
	v_add_u32_e32 v122, 0x800, v142
	v_cvt_pk_bf16_f32 v121, v114, v115
	v_add_u32_e32 v114, 0x1000, v142
	v_cvt_pk_bf16_f32 v113, v106, v107
	v_add_u32_e32 v106, 0x1800, v142
	v_cvt_pk_bf16_f32 v105, v98, v99
	v_add_u32_e32 v98, 0x2000, v142
	v_cvt_pk_bf16_f32 v95, v88, v89
	v_add_u32_e32 v88, 0x2800, v142
	v_cvt_pk_bf16_f32 v87, v80, v81
	v_add_u32_e32 v80, 0x3000, v142
	v_min_f32_e32 v11, 0x7149f2ca, v11
	v_min_f32_e32 v13, 0x7149f2ca, v13
	global_store_dwordx4 v142, v[126:129], s[54:55] sc1
	global_store_dwordx4 v122, v[118:121], s[54:55] sc1
	global_store_dwordx4 v114, v[110:113], s[54:55] sc1
	global_store_dwordx4 v106, v[102:105], s[54:55] sc1
; __device__ __forceinline__ unsigned cvt_pk_bf16(float lo, float hi) { f32x2_t v = {lo, hi}; bf16x2_t b = __builtin_convertvector(v, bf16x2_t); return __builtin_bit_cast(unsigned, b); }
; #define EPI_FENCE() asm volatile("" ::: "memory")
; #define EPI_LANE() int t__ = threadIdx.x; asm volatile("" : "+v"(t__)); const int wid__ = __builtin_amdgcn_readfirstlane(t__ >> 6); wr = wid__ >> 2; wc = wid__ & 3; fr = t__ & 15; fq = (t__ & 63) >> 4
;     template <int MODE> __device__ __forceinline__ void run(const f32x4 (&acc)[2][2][4][2], const Unit& u, int wr, int wc, int fr, int fq) const {
;         EPI_LANE();
;         const int pn = u.pn, colt = pn * BM, t = colt >> 9;
;         char* base = (MODE == 2) ? (char*)(O + (size_t)6 * ((size_t)MTOK * 512)) + ((size_t)(((pn - 12) * 128 + u.pm) * 8 + wid__)) * 16384
;                                  : (char*)(O + (size_t)t * ((size_t)MTOK * 512) + (size_t)u.pm * BM * 512 + (colt & 511));
;         unsigned off0 = (MODE == 2) ? (unsigned)((t__ & 63) * 16) : (unsigned)((wr * 64 + fr) * 512 + wc * 32 + 8 * fq) * 2u; asm volatile("" : "+v"(off0));
; #pragma unroll
;         for (int bj = 0; bj < 2; ++bj) {
; #pragma unroll
;             for (int ai = 0; ai < 2; ++ai)
; #pragma unroll
;                 for (int m = 0; m < 4; ++m) { const unsigned off = off0 + ((MODE == 2) ? (unsigned)(((ai * 4 + m) * 2 + bj) * 1024) : (unsigned)((ai * HALF + m * 16) * 512 + bj * HALF) * 2u);
;                     const f32x4 v0 = acc[ai][bj][m][0], v1 = acc[ai][bj][m][1];
;                     u32x4 w; w.x = cvt_pk_bf16(actf<MODE>(v0[0]), actf<MODE>(v0[1])); w.y = cvt_pk_bf16(actf<MODE>(v0[2]), actf<MODE>(v0[3]));
;                     w.z = cvt_pk_bf16(actf<MODE>(v1[0]), actf<MODE>(v1[1])); w.w = cvt_pk_bf16(actf<MODE>(v1[2]), actf<MODE>(v1[3]));
;                     *(u32x4*)(base + off) = w; }
;             EPI_FENCE();
;         }
;     }
	global_store_dwordx4 v98, v[92:95], s[54:55] sc1
	global_store_dwordx4 v88, v[84:87], s[54:55] sc1
	global_store_dwordx4 v80, v[76:79], s[54:55] sc1
	v_add_u32_e32 v12, 0x400, v142
	v_cvt_pk_bf16_f32 v11, v11, v13
	global_store_dwordx4 v12, v[8:11], s[54:55] sc1
	v_mul_f32_e32 v13, 0xbfb8aa3b, v57
	v_exp_f32_e32 v13, v13
	v_mul_f32_e32 v8, 0xbfb8aa3b, v60
	v_mul_f32_e32 v9, 0xbfb8aa3b, v61
	v_exp_f32_e32 v8, v8
	v_exp_f32_e32 v9, v9
	v_mul_f32_e32 v10, 0xbfb8aa3b, v62
	v_mul_f32_e32 v11, 0xbfb8aa3b, v63
	v_exp_f32_e32 v10, v10
	v_exp_f32_e32 v11, v11
	v_add_f32_e32 v8, 1.0, v8
	v_add_f32_e32 v9, 1.0, v9
	v_min_f32_e32 v8, 0x7149f2ca, v8
	v_min_f32_e32 v9, 0x7149f2ca, v9
	v_cvt_pk_bf16_f32 v8, v8, v9
	v_add_f32_e32 v9, 1.0, v10
	v_add_f32_e32 v10, 1.0, v11
	v_mul_f32_e32 v11, 0xbfb8aa3b, v56
	v_exp_f32_e32 v11, v11
	v_min_f32_e32 v9, 0x7149f2ca, v9
	v_min_f32_e32 v10, 0x7149f2ca, v10
	v_cvt_pk_bf16_f32 v9, v9, v10
	v_add_f32_e32 v10, 1.0, v11
	v_add_f32_e32 v11, 1.0, v13
	v_mul_f32_e32 v13, 0xbfb8aa3b, v58
	v_mul_f32_e32 v14, 0xbfb8aa3b, v59
	v_exp_f32_e32 v13, v13
	v_exp_f32_e32 v14, v14
	v_min_f32_e32 v10, 0x7149f2ca, v10
	v_min_f32_e32 v11, 0x7149f2ca, v11
	v_cvt_pk_bf16_f32 v10, v10, v11
	v_add_f32_e32 v11, 1.0, v13
	v_add_f32_e32 v13, 1.0, v14
	v_min_f32_e32 v11, 0x7149f2ca, v11
	v_min_f32_e32 v13, 0x7149f2ca, v13
	v_add_u32_e32 v12, 0xc00, v142
	v_cvt_pk_bf16_f32 v11, v11, v13
	global_store_dwordx4 v12, v[8:11], s[54:55] sc1
	v_mul_f32_e32 v13, 0xbfb8aa3b, v49
	v_exp_f32_e32 v13, v13
	v_mul_f32_e32 v8, 0xbfb8aa3b, v52
	v_mul_f32_e32 v9, 0xbfb8aa3b, v53
	v_exp_f32_e32 v8, v8
	v_exp_f32_e32 v9, v9
	v_mul_f32_e32 v10, 0xbfb8aa3b, v54
	v_mul_f32_e32 v11, 0xbfb8aa3b, v55
	v_exp_f32_e32 v10, v10
	v_exp_f32_e32 v11, v11
	v_add_f32_e32 v8, 1.0, v8
	v_add_f32_e32 v9, 1.0, v9
	v_min_f32_e32 v8, 0x7149f2ca, v8
	v_min_f32_e32 v9, 0x7149f2ca, v9
	v_cvt_pk_bf16_f32 v8, v8, v9
	v_add_f32_e32 v9, 1.0, v10
	v_add_f32_e32 v10, 1.0, v11
	v_mul_f32_e32 v11, 0xbfb8aa3b, v48
	v_exp_f32_e32 v11, v11
	v_min_f32_e32 v9, 0x7149f2ca, v9
	v_min_f32_e32 v10, 0x7149f2ca, v10
	v_cvt_pk_bf16_f32 v9, v9, v10
	v_add_f32_e32 v10, 1.0, v11
	v_add_f32_e32 v11, 1.0, v13
	v_mul_f32_e32 v13, 0xbfb8aa3b, v50
	v_mul_f32_e32 v14, 0xbfb8aa3b, v51
	v_exp_f32_e32 v13, v13
	v_exp_f32_e32 v14, v14
	v_min_f32_e32 v10, 0x7149f2ca, v10
	v_min_f32_e32 v11, 0x7149f2ca, v11
	v_cvt_pk_bf16_f32 v10, v10, v11
	v_add_f32_e32 v11, 1.0, v13
	v_add_f32_e32 v13, 1.0, v14
	v_min_f32_e32 v11, 0x7149f2ca, v11
	v_min_f32_e32 v13, 0x7149f2ca, v13
	v_add_u32_e32 v12, 0x1400, v142
	v_cvt_pk_bf16_f32 v11, v11, v13
	global_store_dwordx4 v12, v[8:11], s[54:55] sc1
	v_mul_f32_e32 v13, 0xbfb8aa3b, v41
	v_exp_f32_e32 v13, v13
	v_mul_f32_e32 v8, 0xbfb8aa3b, v44
	v_mul_f32_e32 v9, 0xbfb8aa3b, v45
	v_exp_f32_e32 v8, v8
	v_exp_f32_e32 v9, v9
	v_mul_f32_e32 v10, 0xbfb8aa3b, v46
	v_mul_f32_e32 v11, 0xbfb8aa3b, v47
	v_exp_f32_e32 v10, v10
	v_exp_f32_e32 v11, v11
	v_add_f32_e32 v8, 1.0, v8
	v_add_f32_e32 v9, 1.0, v9
	v_min_f32_e32 v8, 0x7149f2ca, v8
	v_min_f32_e32 v9, 0x7149f2ca, v9
	v_cvt_pk_bf16_f32 v8, v8, v9
	v_add_f32_e32 v9, 1.0, v10
	v_add_f32_e32 v10, 1.0, v11
	v_mul_f32_e32 v11, 0xbfb8aa3b, v40
	v_exp_f32_e32 v11, v11
	v_min_f32_e32 v9, 0x7149f2ca, v9
	v_min_f32_e32 v10, 0x7149f2ca, v10
	v_cvt_pk_bf16_f32 v9, v9, v10
	v_add_f32_e32 v10, 1.0, v11
	v_add_f32_e32 v11, 1.0, v13
	v_mul_f32_e32 v13, 0xbfb8aa3b, v42
	v_mul_f32_e32 v14, 0xbfb8aa3b, v43
	v_exp_f32_e32 v13, v13
	v_exp_f32_e32 v14, v14
	v_min_f32_e32 v10, 0x7149f2ca, v10
	v_min_f32_e32 v11, 0x7149f2ca, v11
	v_cvt_pk_bf16_f32 v10, v10, v11
	v_add_f32_e32 v11, 1.0, v13
	v_add_f32_e32 v13, 1.0, v14
	v_min_f32_e32 v11, 0x7149f2ca, v11
	v_min_f32_e32 v13, 0x7149f2ca, v13
	v_add_u32_e32 v12, 0x1c00, v142
	v_cvt_pk_bf16_f32 v11, v11, v13
	global_store_dwordx4 v12, v[8:11], s[54:55] sc1
	v_mul_f32_e32 v13, 0xbfb8aa3b, v33
	v_exp_f32_e32 v13, v13
	v_mul_f32_e32 v8, 0xbfb8aa3b, v36
	v_mul_f32_e32 v9, 0xbfb8aa3b, v37
	v_exp_f32_e32 v8, v8
	v_exp_f32_e32 v9, v9
	v_mul_f32_e32 v10, 0xbfb8aa3b, v38
	v_mul_f32_e32 v11, 0xbfb8aa3b, v39
	v_exp_f32_e32 v10, v10
	v_exp_f32_e32 v11, v11
	v_add_f32_e32 v8, 1.0, v8
	v_add_f32_e32 v9, 1.0, v9
	v_min_f32_e32 v8, 0x7149f2ca, v8
	v_min_f32_e32 v9, 0x7149f2ca, v9
	v_cvt_pk_bf16_f32 v8, v8, v9
; __device__ __forceinline__ unsigned cvt_pk_bf16(float lo, float hi) { f32x2_t v = {lo, hi}; bf16x2_t b = __builtin_convertvector(v, bf16x2_t); return __builtin_bit_cast(unsigned, b); }
; #define EPI_FENCE() asm volatile("" ::: "memory")
; #define EPI_LANE() int t__ = threadIdx.x; asm volatile("" : "+v"(t__)); const int wid__ = __builtin_amdgcn_readfirstlane(t__ >> 6); wr = wid__ >> 2; wc = wid__ & 3; fr = t__ & 15; fq = (t__ & 63) >> 4
;     template <int MODE> __device__ __forceinline__ void run(const f32x4 (&acc)[2][2][4][2], const Unit& u, int wr, int wc, int fr, int fq) const {
;         EPI_LANE();
;         const int pn = u.pn, colt = pn * BM, t = colt >> 9;
;         char* base = (MODE == 2) ? (char*)(O + (size_t)6 * ((size_t)MTOK * 512)) + ((size_t)(((pn - 12) * 128 + u.pm) * 8 + wid__)) * 16384
;                                  : (char*)(O + (size_t)t * ((size_t)MTOK * 512) + (size_t)u.pm * BM * 512 + (colt & 511));
;         unsigned off0 = (MODE == 2) ? (unsigned)((t__ & 63) * 16) : (unsigned)((wr * 64 + fr) * 512 + wc * 32 + 8 * fq) * 2u; asm volatile("" : "+v"(off0));
; #pragma unroll
;         for (int bj = 0; bj < 2; ++bj) {
; #pragma unroll
;             for (int ai = 0; ai < 2; ++ai)
; #pragma unroll
;                 for (int m = 0; m < 4; ++m) { const unsigned off = off0 + ((MODE == 2) ? (unsigned)(((ai * 4 + m) * 2 + bj) * 1024) : (unsigned)((ai * HALF + m * 16) * 512 + bj * HALF) * 2u);
;                     const f32x4 v0 = acc[ai][bj][m][0], v1 = acc[ai][bj][m][1];
;                     u32x4 w; w.x = cvt_pk_bf16(actf<MODE>(v0[0]), actf<MODE>(v0[1])); w.y = cvt_pk_bf16(actf<MODE>(v0[2]), actf<MODE>(v0[3]));
;                     w.z = cvt_pk_bf16(actf<MODE>(v1[0]), actf<MODE>(v1[1])); w.w = cvt_pk_bf16(actf<MODE>(v1[2]), actf<MODE>(v1[3]));
;                     *(u32x4*)(base + off) = w; }
;             EPI_FENCE();
;         }
;     }
	v_add_f32_e32 v9, 1.0, v10
	v_add_f32_e32 v10, 1.0, v11
	v_mul_f32_e32 v11, 0xbfb8aa3b, v32
	v_exp_f32_e32 v11, v11
	v_min_f32_e32 v9, 0x7149f2ca, v9
	v_min_f32_e32 v10, 0x7149f2ca, v10
	v_cvt_pk_bf16_f32 v9, v9, v10
	v_add_f32_e32 v10, 1.0, v11
	v_add_f32_e32 v11, 1.0, v13
	v_mul_f32_e32 v13, 0xbfb8aa3b, v34
	v_mul_f32_e32 v14, 0xbfb8aa3b, v35
	v_exp_f32_e32 v13, v13
	v_exp_f32_e32 v14, v14
	v_min_f32_e32 v10, 0x7149f2ca, v10
	v_min_f32_e32 v11, 0x7149f2ca, v11
	v_cvt_pk_bf16_f32 v10, v10, v11
	v_add_f32_e32 v11, 1.0, v13
	v_add_f32_e32 v13, 1.0, v14
	v_min_f32_e32 v11, 0x7149f2ca, v11
	v_min_f32_e32 v13, 0x7149f2ca, v13
	v_add_u32_e32 v12, 0x2400, v142
	v_cvt_pk_bf16_f32 v11, v11, v13
	global_store_dwordx4 v12, v[8:11], s[54:55] sc1
	v_mul_f32_e32 v13, 0xbfb8aa3b, v25
	v_exp_f32_e32 v13, v13
	v_mul_f32_e32 v8, 0xbfb8aa3b, v28
	v_mul_f32_e32 v9, 0xbfb8aa3b, v29
	v_exp_f32_e32 v8, v8
	v_exp_f32_e32 v9, v9
	v_mul_f32_e32 v10, 0xbfb8aa3b, v30
	v_mul_f32_e32 v11, 0xbfb8aa3b, v31
	v_exp_f32_e32 v10, v10
	v_exp_f32_e32 v11, v11
	v_add_f32_e32 v8, 1.0, v8
	v_add_f32_e32 v9, 1.0, v9
	v_min_f32_e32 v8, 0x7149f2ca, v8
	v_min_f32_e32 v9, 0x7149f2ca, v9
	v_cvt_pk_bf16_f32 v8, v8, v9
	v_add_f32_e32 v9, 1.0, v10
	v_add_f32_e32 v10, 1.0, v11
	v_mul_f32_e32 v11, 0xbfb8aa3b, v24
	v_exp_f32_e32 v11, v11
	v_min_f32_e32 v9, 0x7149f2ca, v9
	v_min_f32_e32 v10, 0x7149f2ca, v10
	v_cvt_pk_bf16_f32 v9, v9, v10
	v_add_f32_e32 v10, 1.0, v11
	v_add_f32_e32 v11, 1.0, v13
	v_mul_f32_e32 v13, 0xbfb8aa3b, v26
	v_mul_f32_e32 v14, 0xbfb8aa3b, v27
	v_exp_f32_e32 v13, v13
	v_exp_f32_e32 v14, v14
	v_min_f32_e32 v10, 0x7149f2ca, v10
	v_min_f32_e32 v11, 0x7149f2ca, v11
	v_cvt_pk_bf16_f32 v10, v10, v11
	v_add_f32_e32 v11, 1.0, v13
	v_add_f32_e32 v13, 1.0, v14
	v_min_f32_e32 v11, 0x7149f2ca, v11
	v_min_f32_e32 v13, 0x7149f2ca, v13
	v_add_u32_e32 v12, 0x2c00, v142
	v_cvt_pk_bf16_f32 v11, v11, v13
	global_store_dwordx4 v12, v[8:11], s[54:55] sc1
	v_mul_f32_e32 v13, 0xbfb8aa3b, v17
	v_exp_f32_e32 v13, v13
	v_mul_f32_e32 v8, 0xbfb8aa3b, v20
	v_mul_f32_e32 v9, 0xbfb8aa3b, v21
	v_exp_f32_e32 v8, v8
	v_exp_f32_e32 v9, v9
	v_mul_f32_e32 v10, 0xbfb8aa3b, v22
	v_mul_f32_e32 v11, 0xbfb8aa3b, v23
	v_exp_f32_e32 v10, v10
	v_exp_f32_e32 v11, v11
	v_add_f32_e32 v8, 1.0, v8
	v_add_f32_e32 v9, 1.0, v9
	v_min_f32_e32 v8, 0x7149f2ca, v8
	v_min_f32_e32 v9, 0x7149f2ca, v9
	v_cvt_pk_bf16_f32 v8, v8, v9
	v_add_f32_e32 v9, 1.0, v10
	v_add_f32_e32 v10, 1.0, v11
	v_mul_f32_e32 v11, 0xbfb8aa3b, v16
	v_exp_f32_e32 v11, v11
	v_mul_f32_e32 v4, 0xbfb8aa3b, v4
	v_mul_f32_e32 v5, 0xbfb8aa3b, v5
	v_exp_f32_e32 v4, v4
	v_exp_f32_e32 v5, v5
	v_min_f32_e32 v9, 0x7149f2ca, v9
	v_min_f32_e32 v10, 0x7149f2ca, v10
	v_mul_f32_e32 v6, 0xbfb8aa3b, v6
	v_mul_f32_e32 v7, 0xbfb8aa3b, v7
	v_mul_f32_e32 v0, 0xbfb8aa3b, v0
	v_mul_f32_e32 v1, 0xbfb8aa3b, v1
	v_cvt_pk_bf16_f32 v9, v9, v10
	v_add_f32_e32 v10, 1.0, v11
	v_add_f32_e32 v11, 1.0, v13
	v_mul_f32_e32 v13, 0xbfb8aa3b, v18
	v_mul_f32_e32 v14, 0xbfb8aa3b, v19
	v_exp_f32_e32 v6, v6
	v_exp_f32_e32 v7, v7
	v_exp_f32_e32 v0, v0
	v_exp_f32_e32 v1, v1
	v_exp_f32_e32 v13, v13
	v_exp_f32_e32 v14, v14
	v_mul_f32_e32 v2, 0xbfb8aa3b, v2
	v_mul_f32_e32 v3, 0xbfb8aa3b, v3
	v_add_f32_e32 v4, 1.0, v4
	v_add_f32_e32 v5, 1.0, v5
	v_exp_f32_e32 v2, v2
	v_exp_f32_e32 v3, v3
	v_min_f32_e32 v4, 0x7149f2ca, v4
	v_min_f32_e32 v5, 0x7149f2ca, v5
	v_min_f32_e32 v10, 0x7149f2ca, v10
	v_min_f32_e32 v11, 0x7149f2ca, v11
	v_cvt_pk_bf16_f32 v4, v4, v5
	v_add_f32_e32 v5, 1.0, v6
	v_add_f32_e32 v6, 1.0, v7
	v_add_f32_e32 v0, 1.0, v0
	v_add_f32_e32 v1, 1.0, v1
	v_cvt_pk_bf16_f32 v10, v10, v11
	v_add_f32_e32 v11, 1.0, v13
	v_add_f32_e32 v13, 1.0, v14
	v_min_f32_e32 v5, 0x7149f2ca, v5
	v_min_f32_e32 v6, 0x7149f2ca, v6
	v_min_f32_e32 v0, 0x7149f2ca, v0
	v_min_f32_e32 v1, 0x7149f2ca, v1
	v_min_f32_e32 v11, 0x7149f2ca, v11
	v_min_f32_e32 v13, 0x7149f2ca, v13
	v_cvt_pk_bf16_f32 v5, v5, v6
	v_cvt_pk_bf16_f32 v6, v0, v1
	v_add_f32_e32 v0, 1.0, v2
	v_add_f32_e32 v1, 1.0, v3
	v_add_u32_e32 v12, 0x3400, v142
	v_cvt_pk_bf16_f32 v11, v11, v13
	v_min_f32_e32 v0, 0x7149f2ca, v0
	v_min_f32_e32 v1, 0x7149f2ca, v1
	global_store_dwordx4 v12, v[8:11], s[54:55] sc1
	v_cvt_pk_bf16_f32 v7, v0, v1
	s_nop 0
	v_add_u32_e32 v8, 0x3c00, v142
	global_store_dwordx4 v8, v[4:7], s[54:55] sc1

; __device__ __forceinline__ unsigned cvt_pk_bf16(float lo, float hi) { f32x2_t v = {lo, hi}; bf16x2_t b = __builtin_convertvector(v, bf16x2_t); return __builtin_bit_cast(unsigned, b); }
; #define EPI_FENCE() asm volatile("" ::: "memory")
; #define EPI_LANE() int t__ = threadIdx.x; asm volatile("" : "+v"(t__)); const int wid__ = __builtin_amdgcn_readfirstlane(t__ >> 6); wr = wid__ >> 2; wc = wid__ & 3; fr = t__ & 15; fq = (t__ & 63) >> 4
;     template <int MODE> __device__ __forceinline__ void run(const f32x4 (&acc)[2][2][4][2], const Unit& u, int wr, int wc, int fr, int fq) const {
;         EPI_LANE();
;         const int pn = u.pn, colt = pn * BM, t = colt >> 9;
;         char* base = (MODE == 2) ? (char*)(O + (size_t)6 * ((size_t)MTOK * 512)) + ((size_t)(((pn - 12) * 128 + u.pm) * 8 + wid__)) * 16384
;                                  : (char*)(O + (size_t)t * ((size_t)MTOK * 512) + (size_t)u.pm * BM * 512 + (colt & 511));
;         unsigned off0 = (MODE == 2) ? (unsigned)((t__ & 63) * 16) : (unsigned)((wr * 64 + fr) * 512 + wc * 32 + 8 * fq) * 2u; asm volatile("" : "+v"(off0));
; #pragma unroll
;         for (int bj = 0; bj < 2; ++bj) {
; #pragma unroll
;             for (int ai = 0; ai < 2; ++ai)
; #pragma unroll
;                 for (int m = 0; m < 4; ++m) { const unsigned off = off0 + ((MODE == 2) ? (unsigned)(((ai * 4 + m) * 2 + bj) * 1024) : (unsigned)((ai * HALF + m * 16) * 512 + bj * HALF) * 2u);
;                     const f32x4 v0 = acc[ai][bj][m][0], v1 = acc[ai][bj][m][1];
;                     u32x4 w; w.x = cvt_pk_bf16(actf<MODE>(v0[0]), actf<MODE>(v0[1])); w.y = cvt_pk_bf16(actf<MODE>(v0[2]), actf<MODE>(v0[3]));
;                     w.z = cvt_pk_bf16(actf<MODE>(v1[0]), actf<MODE>(v1[1])); w.w = cvt_pk_bf16(actf<MODE>(v1[2]), actf<MODE>(v1[3]));
;                     *(u32x4*)(base + off) = w; }
;             EPI_FENCE();
;         }
;     }
.LBB0_411:
	s_and_b32 s55, s72, -2
	s_lshl_b32 s62, s72, 8
	s_cmp_lg_u32 s55, 2
	s_cbranch_scc0 .LBB0_413
	s_ashr_i32 s60, s72, 1
	s_ashr_i32 s61, s60, 31
	s_lshl_b64 s[60:61], s[60:61], 25
	s_add_u32 s73, s90, s60
	s_addc_u32 s74, s91, s61
	s_ashr_i32 s55, s54, 31
	s_lshl_b64 s[60:61], s[54:55], 18
	s_add_u32 s55, s73, s60
	s_addc_u32 s61, s74, s61
	s_and_b32 s60, s62, 0x100
	v_mov_b32_e32 v142, v212
	s_lshl_b32 s60, s60, 1
	s_add_u32 s60, s55, s60
	v_readfirstlane_b32 s63, v142
	s_addc_u32 s61, s61, 0
	s_lshr_b32 s55, s63, 2
	s_and_b32 s55, s55, 0x3fffc0
	v_and_or_b32 v143, v142, 15, s55
	v_lshlrev_b32_e32 v143, 10, v143
	s_and_b32 s55, s63, 0xc0
	v_and_b32_e32 v142, 48, v142
	v_or3_b32 v146, v143, s55, v142
	v_cvt_pk_bf16_f32 v142, v126, v127
	v_cvt_pk_bf16_f32 v143, v128, v129
	v_cvt_pk_bf16_f32 v144, v122, v123
	v_cvt_pk_bf16_f32 v145, v124, v125
	global_store_dwordx4 v146, v[142:145], s[60:61] sc1
	v_add_u32_e32 v147, 0x4000, v146
	s_nop 0
	v_cvt_pk_bf16_f32 v142, v118, v119
	v_cvt_pk_bf16_f32 v143, v120, v121
	v_cvt_pk_bf16_f32 v144, v114, v115
	v_cvt_pk_bf16_f32 v145, v116, v117
	global_store_dwordx4 v147, v[142:145], s[60:61] sc1
	v_add_u32_e32 v147, 0x8000, v146
	s_nop 0
	v_cvt_pk_bf16_f32 v142, v110, v111
	v_cvt_pk_bf16_f32 v143, v112, v113
	v_cvt_pk_bf16_f32 v144, v106, v107
	v_cvt_pk_bf16_f32 v145, v108, v109
	global_store_dwordx4 v147, v[142:145], s[60:61] sc1
	v_add_u32_e32 v147, 0xc000, v146
	s_nop 0
	v_cvt_pk_bf16_f32 v142, v102, v103
	v_cvt_pk_bf16_f32 v143, v104, v105
	v_cvt_pk_bf16_f32 v144, v98, v99
	v_cvt_pk_bf16_f32 v145, v100, v101
	global_store_dwordx4 v147, v[142:145], s[60:61] sc1
	v_add_u32_e32 v147, 0x20000, v146
	s_nop 0
	v_cvt_pk_bf16_f32 v142, v92, v93
	v_cvt_pk_bf16_f32 v143, v94, v95
	v_cvt_pk_bf16_f32 v144, v88, v89
	v_cvt_pk_bf16_f32 v145, v90, v91
	global_store_dwordx4 v147, v[142:145], s[60:61] sc1
	v_add_u32_e32 v147, 0x24000, v146
	s_nop 0
	v_cvt_pk_bf16_f32 v142, v84, v85
	v_cvt_pk_bf16_f32 v143, v86, v87
	v_cvt_pk_bf16_f32 v144, v80, v81
	v_cvt_pk_bf16_f32 v145, v82, v83
	global_store_dwordx4 v147, v[142:145], s[60:61] sc1
	v_add_u32_e32 v147, 0x28000, v146
	s_nop 0
	v_cvt_pk_bf16_f32 v142, v76, v77
	v_cvt_pk_bf16_f32 v143, v78, v79
	v_cvt_pk_bf16_f32 v144, v72, v73
	v_cvt_pk_bf16_f32 v145, v74, v75
	global_store_dwordx4 v147, v[142:145], s[60:61] sc1
	v_add_u32_e32 v147, 0x2c000, v146
	s_nop 0
	v_cvt_pk_bf16_f32 v142, v12, v13
	v_cvt_pk_bf16_f32 v143, v14, v15
	v_cvt_pk_bf16_f32 v144, v8, v9
	v_cvt_pk_bf16_f32 v145, v10, v11
	global_store_dwordx4 v147, v[142:145], s[60:61] sc1
	v_add_u32_e32 v147, 0x100, v146
	s_nop 0
	v_cvt_pk_bf16_f32 v142, v68, v69
	v_cvt_pk_bf16_f32 v143, v70, v71
	v_cvt_pk_bf16_f32 v144, v64, v65
	v_cvt_pk_bf16_f32 v145, v66, v67
	global_store_dwordx4 v147, v[142:145], s[60:61] sc1
	v_add_u32_e32 v147, 0x4100, v146
	s_nop 0
	v_cvt_pk_bf16_f32 v142, v60, v61
	v_cvt_pk_bf16_f32 v143, v62, v63
	v_cvt_pk_bf16_f32 v144, v56, v57
	v_cvt_pk_bf16_f32 v145, v58, v59
	global_store_dwordx4 v147, v[142:145], s[60:61] sc1
	v_add_u32_e32 v147, 0x8100, v146
	s_nop 0
	v_cvt_pk_bf16_f32 v142, v52, v53
	v_cvt_pk_bf16_f32 v143, v54, v55
	v_cvt_pk_bf16_f32 v144, v48, v49
	v_cvt_pk_bf16_f32 v145, v50, v51
	global_store_dwordx4 v147, v[142:145], s[60:61] sc1
	v_add_u32_e32 v147, 0xc100, v146
	s_nop 0
	v_cvt_pk_bf16_f32 v142, v44, v45
	v_cvt_pk_bf16_f32 v143, v46, v47
	v_cvt_pk_bf16_f32 v144, v40, v41
	v_cvt_pk_bf16_f32 v145, v42, v43
	global_store_dwordx4 v147, v[142:145], s[60:61] sc1
	v_add_u32_e32 v147, 0x20100, v146
	s_nop 0
	v_cvt_pk_bf16_f32 v142, v36, v37
	v_cvt_pk_bf16_f32 v143, v38, v39
	v_cvt_pk_bf16_f32 v144, v32, v33
	v_cvt_pk_bf16_f32 v145, v34, v35
	global_store_dwordx4 v147, v[142:145], s[60:61] sc1
	v_add_u32_e32 v147, 0x24100, v146
	s_nop 0
	v_cvt_pk_bf16_f32 v142, v28, v29
	v_cvt_pk_bf16_f32 v143, v30, v31
	v_cvt_pk_bf16_f32 v144, v24, v25
	v_cvt_pk_bf16_f32 v145, v26, v27
	global_store_dwordx4 v147, v[142:145], s[60:61] sc1
	v_add_u32_e32 v147, 0x28100, v146
	v_add_u32_e32 v146, 0x2c100, v146
	v_cvt_pk_bf16_f32 v142, v20, v21
	v_cvt_pk_bf16_f32 v143, v22, v23
	v_cvt_pk_bf16_f32 v144, v16, v17
	v_cvt_pk_bf16_f32 v145, v18, v19
	global_store_dwordx4 v147, v[142:145], s[60:61] sc1
	s_nop 1
	v_cvt_pk_bf16_f32 v142, v4, v5
	v_cvt_pk_bf16_f32 v143, v6, v7
	v_cvt_pk_bf16_f32 v144, v0, v1
	v_cvt_pk_bf16_f32 v145, v2, v3
	global_store_dwordx4 v146, v[142:145], s[60:61] sc1
	s_mov_b64 s[60:61], 0
; __device__ __forceinline__ unsigned cvt_pk_bf16(float lo, float hi) { f32x2_t v = {lo, hi}; bf16x2_t b = __builtin_convertvector(v, bf16x2_t); return __builtin_bit_cast(unsigned, b); }
; #define EPI_FENCE() asm volatile("" ::: "memory")
; #define EPI_LANE() int t__ = threadIdx.x; asm volatile("" : "+v"(t__)); const int wid__ = __builtin_amdgcn_readfirstlane(t__ >> 6); wr = wid__ >> 2; wc = wid__ & 3; fr = t__ & 15; fq = (t__ & 63) >> 4
;     template <int MODE> __device__ __forceinline__ void run(const f32x4 (&acc)[2][2][4][2], const Unit& u, int wr, int wc, int fr, int fq) const {
;         EPI_LANE();
;         const int pn = u.pn, colt = pn * BM, t = colt >> 9;
;         char* base = (MODE == 2) ? (char*)(O + (size_t)6 * ((size_t)MTOK * 512)) + ((size_t)(((pn - 12) * 128 + u.pm) * 8 + wid__)) * 16384
;                                  : (char*)(O + (size_t)t * ((size_t)MTOK * 512) + (size_t)u.pm * BM * 512 + (colt & 511));
;         unsigned off0 = (MODE == 2) ? (unsigned)((t__ & 63) * 16) : (unsigned)((wr * 64 + fr) * 512 + wc * 32 + 8 * fq) * 2u; asm volatile("" : "+v"(off0));
; #pragma unroll
;         for (int bj = 0; bj < 2; ++bj) {
; #pragma unroll
;             for (int ai = 0; ai < 2; ++ai)
; #pragma unroll
;                 for (int m = 0; m < 4; ++m) { const unsigned off = off0 + ((MODE == 2) ? (unsigned)(((ai * 4 + m) * 2 + bj) * 1024) : (unsigned)((ai * HALF + m * 16) * 512 + bj * HALF) * 2u);
;                     const f32x4 v0 = acc[ai][bj][m][0], v1 = acc[ai][bj][m][1];
;                     u32x4 w; w.x = cvt_pk_bf16(actf<MODE>(v0[0]), actf<MODE>(v0[1])); w.y = cvt_pk_bf16(actf<MODE>(v0[2]), actf<MODE>(v0[3]));
;                     w.z = cvt_pk_bf16(actf<MODE>(v1[0]), actf<MODE>(v1[1])); w.w = cvt_pk_bf16(actf<MODE>(v1[2]), actf<MODE>(v1[3]));
;                     *(u32x4*)(base + off) = w; }
;             EPI_FENCE();
;         }
;     }
.LBB0_413:
	s_andn2_b64 vcc, exec, s[60:61]
	s_cbranch_vccnz .LBB0_415
	s_ashr_i32 s55, s54, 31
	s_lshl_b64 s[60:61], s[54:55], 18
	s_add_u32 s55, s89, s60
	s_addc_u32 s61, s3, s61
	s_and_b32 s60, s62, 0x100
	v_mov_b32_e32 v142, v212
	s_lshl_b32 s60, s60, 1
	s_add_u32 s60, s55, s60
	v_readfirstlane_b32 s63, v142
	s_addc_u32 s61, s61, 0
	s_lshr_b32 s55, s63, 2
	s_and_b32 s55, s55, 0x3fffc0
	v_and_or_b32 v143, v142, 15, s55
	v_lshlrev_b32_e32 v143, 10, v143
	s_and_b32 s55, s63, 0xc0
	v_and_b32_e32 v142, 48, v142
	s_mov_b32 s24, 0x3e38aa3b
	v_or3_b32 v148, v143, s55, v142
	v_pk_mul_f32 v[142:143], v[126:127], s[24:25] op_sel_hi:[1,0]
	v_pk_mul_f32 v[144:145], v[128:129], s[24:25] op_sel_hi:[1,0]
	v_cvt_pk_bf16_f32 v142, v142, v143
	v_cvt_pk_bf16_f32 v143, v144, v145
	v_pk_mul_f32 v[144:145], v[122:123], s[24:25] op_sel_hi:[1,0]
	v_pk_mul_f32 v[146:147], v[124:125], s[24:25] op_sel_hi:[1,0]
	v_cvt_pk_bf16_f32 v144, v144, v145
	v_cvt_pk_bf16_f32 v145, v146, v147
	global_store_dwordx4 v148, v[142:145], s[60:61] sc1
	v_pk_mul_f32 v[146:147], v[116:117], s[24:25] op_sel_hi:[1,0]
	v_add_u32_e32 v149, 0x4000, v148
	v_pk_mul_f32 v[142:143], v[118:119], s[24:25] op_sel_hi:[1,0]
	v_pk_mul_f32 v[144:145], v[120:121], s[24:25] op_sel_hi:[1,0]
	v_cvt_pk_bf16_f32 v142, v142, v143
	v_cvt_pk_bf16_f32 v143, v144, v145
	v_pk_mul_f32 v[144:145], v[114:115], s[24:25] op_sel_hi:[1,0]
	s_nop 0
	v_cvt_pk_bf16_f32 v144, v144, v145
	v_cvt_pk_bf16_f32 v145, v146, v147
	global_store_dwordx4 v149, v[142:145], s[60:61] sc1
	v_pk_mul_f32 v[146:147], v[108:109], s[24:25] op_sel_hi:[1,0]
	v_add_u32_e32 v149, 0x8000, v148
	v_pk_mul_f32 v[142:143], v[110:111], s[24:25] op_sel_hi:[1,0]
	v_pk_mul_f32 v[144:145], v[112:113], s[24:25] op_sel_hi:[1,0]
	v_cvt_pk_bf16_f32 v142, v142, v143
	v_cvt_pk_bf16_f32 v143, v144, v145
	v_pk_mul_f32 v[144:145], v[106:107], s[24:25] op_sel_hi:[1,0]
	s_nop 0
	v_cvt_pk_bf16_f32 v144, v144, v145
	v_cvt_pk_bf16_f32 v145, v146, v147
	global_store_dwordx4 v149, v[142:145], s[60:61] sc1
	v_pk_mul_f32 v[146:147], v[100:101], s[24:25] op_sel_hi:[1,0]
	v_add_u32_e32 v149, 0xc000, v148
	v_pk_mul_f32 v[142:143], v[102:103], s[24:25] op_sel_hi:[1,0]
	v_pk_mul_f32 v[144:145], v[104:105], s[24:25] op_sel_hi:[1,0]
	v_cvt_pk_bf16_f32 v142, v142, v143
	v_cvt_pk_bf16_f32 v143, v144, v145
	v_pk_mul_f32 v[144:145], v[98:99], s[24:25] op_sel_hi:[1,0]
	s_nop 0
	v_cvt_pk_bf16_f32 v144, v144, v145
	v_cvt_pk_bf16_f32 v145, v146, v147
	global_store_dwordx4 v149, v[142:145], s[60:61] sc1
	v_pk_mul_f32 v[146:147], v[90:91], s[24:25] op_sel_hi:[1,0]
	v_add_u32_e32 v149, 0x20000, v148
	v_pk_mul_f32 v[142:143], v[92:93], s[24:25] op_sel_hi:[1,0]
	v_pk_mul_f32 v[144:145], v[94:95], s[24:25] op_sel_hi:[1,0]
	v_cvt_pk_bf16_f32 v142, v142, v143
	v_cvt_pk_bf16_f32 v143, v144, v145
	v_pk_mul_f32 v[144:145], v[88:89], s[24:25] op_sel_hi:[1,0]
	s_nop 0
	v_cvt_pk_bf16_f32 v144, v144, v145
	v_cvt_pk_bf16_f32 v145, v146, v147
	global_store_dwordx4 v149, v[142:145], s[60:61] sc1
	v_pk_mul_f32 v[146:147], v[82:83], s[24:25] op_sel_hi:[1,0]
	v_add_u32_e32 v149, 0x24000, v148
	v_pk_mul_f32 v[142:143], v[84:85], s[24:25] op_sel_hi:[1,0]
	v_pk_mul_f32 v[144:145], v[86:87], s[24:25] op_sel_hi:[1,0]
	v_cvt_pk_bf16_f32 v142, v142, v143
	v_cvt_pk_bf16_f32 v143, v144, v145
	v_pk_mul_f32 v[144:145], v[80:81], s[24:25] op_sel_hi:[1,0]
	s_nop 0
	v_cvt_pk_bf16_f32 v144, v144, v145
	v_cvt_pk_bf16_f32 v145, v146, v147
	global_store_dwordx4 v149, v[142:145], s[60:61] sc1
	v_pk_mul_f32 v[146:147], v[74:75], s[24:25] op_sel_hi:[1,0]
	v_add_u32_e32 v149, 0x28000, v148
	v_pk_mul_f32 v[142:143], v[76:77], s[24:25] op_sel_hi:[1,0]
	v_pk_mul_f32 v[144:145], v[78:79], s[24:25] op_sel_hi:[1,0]
	v_cvt_pk_bf16_f32 v142, v142, v143
	v_cvt_pk_bf16_f32 v143, v144, v145
	v_pk_mul_f32 v[144:145], v[72:73], s[24:25] op_sel_hi:[1,0]
	s_nop 0
	v_cvt_pk_bf16_f32 v144, v144, v145
	v_cvt_pk_bf16_f32 v145, v146, v147
	global_store_dwordx4 v149, v[142:145], s[60:61] sc1
	v_pk_mul_f32 v[146:147], v[10:11], s[24:25] op_sel_hi:[1,0]
	v_add_u32_e32 v149, 0x2c000, v148
	v_pk_mul_f32 v[142:143], v[12:13], s[24:25] op_sel_hi:[1,0]
	v_pk_mul_f32 v[144:145], v[14:15], s[24:25] op_sel_hi:[1,0]
; __device__ __forceinline__ unsigned cvt_pk_bf16(float lo, float hi) { f32x2_t v = {lo, hi}; bf16x2_t b = __builtin_convertvector(v, bf16x2_t); return __builtin_bit_cast(unsigned, b); }
; #define EPI_FENCE() asm volatile("" ::: "memory")
; #define EPI_LANE() int t__ = threadIdx.x; asm volatile("" : "+v"(t__)); const int wid__ = __builtin_amdgcn_readfirstlane(t__ >> 6); wr = wid__ >> 2; wc = wid__ & 3; fr = t__ & 15; fq = (t__ & 63) >> 4
;     template <int MODE> __device__ __forceinline__ void run(const f32x4 (&acc)[2][2][4][2], const Unit& u, int wr, int wc, int fr, int fq) const {
;         EPI_LANE();
;         const int pn = u.pn, colt = pn * BM, t = colt >> 9;
;         char* base = (MODE == 2) ? (char*)(O + (size_t)6 * ((size_t)MTOK * 512)) + ((size_t)(((pn - 12) * 128 + u.pm) * 8 + wid__)) * 16384
;                                  : (char*)(O + (size_t)t * ((size_t)MTOK * 512) + (size_t)u.pm * BM * 512 + (colt & 511));
;         unsigned off0 = (MODE == 2) ? (unsigned)((t__ & 63) * 16) : (unsigned)((wr * 64 + fr) * 512 + wc * 32 + 8 * fq) * 2u; asm volatile("" : "+v"(off0));
; #pragma unroll
;         for (int bj = 0; bj < 2; ++bj) {
; #pragma unroll
;             for (int ai = 0; ai < 2; ++ai)
; #pragma unroll
;                 for (int m = 0; m < 4; ++m) { const unsigned off = off0 + ((MODE == 2) ? (unsigned)(((ai * 4 + m) * 2 + bj) * 1024) : (unsigned)((ai * HALF + m * 16) * 512 + bj * HALF) * 2u);
;                     const f32x4 v0 = acc[ai][bj][m][0], v1 = acc[ai][bj][m][1];
;                     u32x4 w; w.x = cvt_pk_bf16(actf<MODE>(v0[0]), actf<MODE>(v0[1])); w.y = cvt_pk_bf16(actf<MODE>(v0[2]), actf<MODE>(v0[3]));
;                     w.z = cvt_pk_bf16(actf<MODE>(v1[0]), actf<MODE>(v1[1])); w.w = cvt_pk_bf16(actf<MODE>(v1[2]), actf<MODE>(v1[3]));
;                     *(u32x4*)(base + off) = w; }
;             EPI_FENCE();
;         }
;     }
	v_cvt_pk_bf16_f32 v142, v142, v143
	v_cvt_pk_bf16_f32 v143, v144, v145
	v_pk_mul_f32 v[144:145], v[8:9], s[24:25] op_sel_hi:[1,0]
	s_nop 0
	v_cvt_pk_bf16_f32 v144, v144, v145
	v_cvt_pk_bf16_f32 v145, v146, v147
	global_store_dwordx4 v149, v[142:145], s[60:61] sc1
	v_pk_mul_f32 v[146:147], v[66:67], s[24:25] op_sel_hi:[1,0]
	v_add_u32_e32 v149, 0x100, v148
	v_pk_mul_f32 v[142:143], v[68:69], s[24:25] op_sel_hi:[1,0]
	v_pk_mul_f32 v[144:145], v[70:71], s[24:25] op_sel_hi:[1,0]
	v_cvt_pk_bf16_f32 v142, v142, v143
	v_cvt_pk_bf16_f32 v143, v144, v145
	v_pk_mul_f32 v[144:145], v[64:65], s[24:25] op_sel_hi:[1,0]
	s_nop 0
	v_cvt_pk_bf16_f32 v144, v144, v145
	v_cvt_pk_bf16_f32 v145, v146, v147
	global_store_dwordx4 v149, v[142:145], s[60:61] sc1
	v_pk_mul_f32 v[146:147], v[58:59], s[24:25] op_sel_hi:[1,0]
	v_add_u32_e32 v149, 0x4100, v148
	v_pk_mul_f32 v[142:143], v[60:61], s[24:25] op_sel_hi:[1,0]
	v_pk_mul_f32 v[144:145], v[62:63], s[24:25] op_sel_hi:[1,0]
	v_cvt_pk_bf16_f32 v142, v142, v143
	v_cvt_pk_bf16_f32 v143, v144, v145
	v_pk_mul_f32 v[144:145], v[56:57], s[24:25] op_sel_hi:[1,0]
	s_nop 0
	v_cvt_pk_bf16_f32 v144, v144, v145
	v_cvt_pk_bf16_f32 v145, v146, v147
	global_store_dwordx4 v149, v[142:145], s[60:61] sc1
	v_pk_mul_f32 v[146:147], v[50:51], s[24:25] op_sel_hi:[1,0]
	v_add_u32_e32 v149, 0x8100, v148
	v_pk_mul_f32 v[142:143], v[52:53], s[24:25] op_sel_hi:[1,0]
	v_pk_mul_f32 v[144:145], v[54:55], s[24:25] op_sel_hi:[1,0]
	v_cvt_pk_bf16_f32 v142, v142, v143
	v_cvt_pk_bf16_f32 v143, v144, v145
	v_pk_mul_f32 v[144:145], v[48:49], s[24:25] op_sel_hi:[1,0]
	s_nop 0
	v_cvt_pk_bf16_f32 v144, v144, v145
	v_cvt_pk_bf16_f32 v145, v146, v147
	global_store_dwordx4 v149, v[142:145], s[60:61] sc1
	v_pk_mul_f32 v[146:147], v[42:43], s[24:25] op_sel_hi:[1,0]
	v_add_u32_e32 v149, 0xc100, v148
	v_pk_mul_f32 v[142:143], v[44:45], s[24:25] op_sel_hi:[1,0]
	v_pk_mul_f32 v[144:145], v[46:47], s[24:25] op_sel_hi:[1,0]
	v_cvt_pk_bf16_f32 v142, v142, v143
	v_cvt_pk_bf16_f32 v143, v144, v145
	v_pk_mul_f32 v[144:145], v[40:41], s[24:25] op_sel_hi:[1,0]
	s_nop 0
	v_cvt_pk_bf16_f32 v144, v144, v145
	v_cvt_pk_bf16_f32 v145, v146, v147
	global_store_dwordx4 v149, v[142:145], s[60:61] sc1
	v_pk_mul_f32 v[146:147], v[34:35], s[24:25] op_sel_hi:[1,0]
	v_add_u32_e32 v149, 0x20100, v148
	v_pk_mul_f32 v[142:143], v[36:37], s[24:25] op_sel_hi:[1,0]
	v_pk_mul_f32 v[144:145], v[38:39], s[24:25] op_sel_hi:[1,0]
	v_cvt_pk_bf16_f32 v142, v142, v143
	v_cvt_pk_bf16_f32 v143, v144, v145
	v_pk_mul_f32 v[144:145], v[32:33], s[24:25] op_sel_hi:[1,0]
	s_nop 0
	v_cvt_pk_bf16_f32 v144, v144, v145
	v_cvt_pk_bf16_f32 v145, v146, v147
	global_store_dwordx4 v149, v[142:145], s[60:61] sc1
	v_pk_mul_f32 v[146:147], v[26:27], s[24:25] op_sel_hi:[1,0]
	v_add_u32_e32 v149, 0x24100, v148
	v_pk_mul_f32 v[142:143], v[28:29], s[24:25] op_sel_hi:[1,0]
	v_pk_mul_f32 v[144:145], v[30:31], s[24:25] op_sel_hi:[1,0]
	v_cvt_pk_bf16_f32 v142, v142, v143
	v_cvt_pk_bf16_f32 v143, v144, v145
	v_pk_mul_f32 v[144:145], v[24:25], s[24:25] op_sel_hi:[1,0]
	s_nop 0
	v_cvt_pk_bf16_f32 v144, v144, v145
	v_cvt_pk_bf16_f32 v145, v146, v147
	global_store_dwordx4 v149, v[142:145], s[60:61] sc1
	v_pk_mul_f32 v[146:147], v[18:19], s[24:25] op_sel_hi:[1,0]
	v_add_u32_e32 v149, 0x28100, v148
	v_pk_mul_f32 v[142:143], v[20:21], s[24:25] op_sel_hi:[1,0]
	v_pk_mul_f32 v[144:145], v[22:23], s[24:25] op_sel_hi:[1,0]
	v_cvt_pk_bf16_f32 v142, v142, v143
	v_cvt_pk_bf16_f32 v143, v144, v145
	v_pk_mul_f32 v[144:145], v[16:17], s[24:25] op_sel_hi:[1,0]
	v_add_u32_e32 v148, 0x2c100, v148
	v_cvt_pk_bf16_f32 v144, v144, v145
	v_cvt_pk_bf16_f32 v145, v146, v147
	global_store_dwordx4 v149, v[142:145], s[60:61] sc1
	v_pk_mul_f32 v[146:147], v[2:3], s[24:25] op_sel_hi:[1,0]
	s_nop 0
	v_pk_mul_f32 v[142:143], v[4:5], s[24:25] op_sel_hi:[1,0]
	v_pk_mul_f32 v[144:145], v[6:7], s[24:25] op_sel_hi:[1,0]
	v_cvt_pk_bf16_f32 v142, v142, v143
	v_cvt_pk_bf16_f32 v143, v144, v145
	v_pk_mul_f32 v[144:145], v[0:1], s[24:25] op_sel_hi:[1,0]
	s_nop 0
	v_cvt_pk_bf16_f32 v144, v144, v145
	v_cvt_pk_bf16_f32 v145, v146, v147
	global_store_dwordx4 v148, v[142:145], s[60:61] sc1
